# P2a qk_norm rewritten: gains loaded once, q/k of all 8 items per thread loaded together, one drain
# speedup vs baseline: 1.0477x; 1.0051x over previous
.LBB0_261:
	v_and_b32_e32 v41, 31, v4
	v_and_b32_e32 v42, 7, v4
	v_lshrrev_b32_e32 v40, 5, v4
	v_lshlrev_b32_e32 v41, 4, v41
	v_lshlrev_b32_e32 v42, 5, v42
	global_load_dwordx4 v[212:215], v42, s[0:1]
	global_load_dwordx4 v[216:219], v42, s[0:1] offset:16
	global_load_dwordx4 v[220:223], v42, s[4:5]
	global_load_dwordx4 v[224:227], v42, s[4:5] offset:16
	s_lshr_b32 s12, s97, 5
	v_mad_u32_u24 v108, v40, s75, v41
	v_add_u32_e32 v40, s12, v40
	global_load_dwordx4 v[44:47], v108, s[36:37] offset:2048
	global_load_dwordx4 v[48:51], v108, s[36:37] offset:2560
	v_mad_u32_u24 v109, v40, s75, v41
	v_add_u32_e32 v40, s12, v40
	global_load_dwordx4 v[52:55], v109, s[36:37] offset:2048
	global_load_dwordx4 v[56:59], v109, s[36:37] offset:2560
	v_mad_u32_u24 v110, v40, s75, v41
	v_add_u32_e32 v40, s12, v40
	global_load_dwordx4 v[60:63], v110, s[36:37] offset:2048
	global_load_dwordx4 v[64:67], v110, s[36:37] offset:2560
	v_mad_u32_u24 v111, v40, s75, v41
	v_add_u32_e32 v40, s12, v40
	global_load_dwordx4 v[68:71], v111, s[36:37] offset:2048
	global_load_dwordx4 v[72:75], v111, s[36:37] offset:2560
	v_mad_u32_u24 v112, v40, s75, v41
	v_add_u32_e32 v40, s12, v40
	global_load_dwordx4 v[76:79], v112, s[36:37] offset:2048
	global_load_dwordx4 v[80:83], v112, s[36:37] offset:2560
	v_mad_u32_u24 v113, v40, s75, v41
	v_add_u32_e32 v40, s12, v40
	global_load_dwordx4 v[84:87], v113, s[36:37] offset:2048
	global_load_dwordx4 v[88:91], v113, s[36:37] offset:2560
	v_mad_u32_u24 v114, v40, s75, v41
	v_add_u32_e32 v40, s12, v40
	global_load_dwordx4 v[92:95], v114, s[36:37] offset:2048
	global_load_dwordx4 v[96:99], v114, s[36:37] offset:2560
	v_mad_u32_u24 v115, v40, s75, v41
	global_load_dwordx4 v[100:103], v115, s[36:37] offset:2048
	global_load_dwordx4 v[104:107], v115, s[36:37] offset:2560
	s_waitcnt vmcnt(0)
	v_lshlrev_b32_e32 v22, 16, v44
	v_and_b32_e32 v23, 0xffff0000, v44
	v_lshlrev_b32_e32 v24, 16, v45
	v_and_b32_e32 v25, 0xffff0000, v45
	v_lshlrev_b32_e32 v26, 16, v46
	v_and_b32_e32 v27, 0xffff0000, v46
	v_lshlrev_b32_e32 v28, 16, v47
	v_and_b32_e32 v29, 0xffff0000, v47
	v_mul_f32_e32 v30, v23, v23
	v_mul_f32_e32 v31, v25, v25
	v_mul_f32_e32 v32, v27, v27
	v_mul_f32_e32 v33, v29, v29
	v_fmac_f32_e32 v30, v22, v22
	v_fmac_f32_e32 v31, v24, v24
	v_fmac_f32_e32 v32, v26, v26
	v_fmac_f32_e32 v33, v28, v28
	v_add_f32_e32 v116, v30, v31
	v_add_f32_e32 v116, v32, v116
	v_add_f32_e32 v116, v33, v116
	v_lshlrev_b32_e32 v22, 16, v48
	v_and_b32_e32 v23, 0xffff0000, v48
	v_lshlrev_b32_e32 v24, 16, v49
	v_and_b32_e32 v25, 0xffff0000, v49
	v_lshlrev_b32_e32 v26, 16, v50
	v_and_b32_e32 v27, 0xffff0000, v50
	v_lshlrev_b32_e32 v28, 16, v51
	v_and_b32_e32 v29, 0xffff0000, v51
	v_mul_f32_e32 v30, v23, v23
	v_mul_f32_e32 v31, v25, v25
	v_mul_f32_e32 v32, v27, v27
	v_mul_f32_e32 v33, v29, v29
	v_fmac_f32_e32 v30, v22, v22
	v_fmac_f32_e32 v31, v24, v24
	v_fmac_f32_e32 v32, v26, v26
	v_fmac_f32_e32 v33, v28, v28
	v_add_f32_e32 v124, v30, v31
	v_add_f32_e32 v124, v32, v124
	v_add_f32_e32 v124, v33, v124
	v_lshlrev_b32_e32 v22, 16, v52
	v_and_b32_e32 v23, 0xffff0000, v52
	v_lshlrev_b32_e32 v24, 16, v53
	v_and_b32_e32 v25, 0xffff0000, v53
	v_lshlrev_b32_e32 v26, 16, v54
	v_and_b32_e32 v27, 0xffff0000, v54
	v_lshlrev_b32_e32 v28, 16, v55
	v_and_b32_e32 v29, 0xffff0000, v55
	v_mul_f32_e32 v30, v23, v23
	v_mul_f32_e32 v31, v25, v25
	v_mul_f32_e32 v32, v27, v27
	v_mul_f32_e32 v33, v29, v29
	v_fmac_f32_e32 v30, v22, v22
	v_fmac_f32_e32 v31, v24, v24
	v_fmac_f32_e32 v32, v26, v26
	v_fmac_f32_e32 v33, v28, v28
	v_add_f32_e32 v117, v30, v31
	v_add_f32_e32 v117, v32, v117
	v_add_f32_e32 v117, v33, v117
	v_lshlrev_b32_e32 v22, 16, v56
	v_and_b32_e32 v23, 0xffff0000, v56
	v_lshlrev_b32_e32 v24, 16, v57
	v_and_b32_e32 v25, 0xffff0000, v57
	v_lshlrev_b32_e32 v26, 16, v58
	v_and_b32_e32 v27, 0xffff0000, v58
	v_lshlrev_b32_e32 v28, 16, v59
	v_and_b32_e32 v29, 0xffff0000, v59
	v_mul_f32_e32 v30, v23, v23
	v_mul_f32_e32 v31, v25, v25
	v_mul_f32_e32 v32, v27, v27
	v_mul_f32_e32 v33, v29, v29
	v_fmac_f32_e32 v30, v22, v22
	v_fmac_f32_e32 v31, v24, v24
	v_fmac_f32_e32 v32, v26, v26
	v_fmac_f32_e32 v33, v28, v28
	v_add_f32_e32 v125, v30, v31
	v_add_f32_e32 v125, v32, v125
	v_add_f32_e32 v125, v33, v125
	v_lshlrev_b32_e32 v22, 16, v60
	v_and_b32_e32 v23, 0xffff0000, v60
	v_lshlrev_b32_e32 v24, 16, v61
	v_and_b32_e32 v25, 0xffff0000, v61
	v_lshlrev_b32_e32 v26, 16, v62
	v_and_b32_e32 v27, 0xffff0000, v62
	v_lshlrev_b32_e32 v28, 16, v63
	v_and_b32_e32 v29, 0xffff0000, v63
	v_mul_f32_e32 v30, v23, v23
	v_mul_f32_e32 v31, v25, v25
	v_mul_f32_e32 v32, v27, v27
	v_mul_f32_e32 v33, v29, v29
	v_fmac_f32_e32 v30, v22, v22
	v_fmac_f32_e32 v31, v24, v24
	v_fmac_f32_e32 v32, v26, v26
	v_fmac_f32_e32 v33, v28, v28
	v_add_f32_e32 v118, v30, v31
	v_add_f32_e32 v118, v32, v118
	v_add_f32_e32 v118, v33, v118
	v_lshlrev_b32_e32 v22, 16, v64
	v_and_b32_e32 v23, 0xffff0000, v64
	v_lshlrev_b32_e32 v24, 16, v65
	v_and_b32_e32 v25, 0xffff0000, v65
	v_lshlrev_b32_e32 v26, 16, v66
	v_and_b32_e32 v27, 0xffff0000, v66
	v_lshlrev_b32_e32 v28, 16, v67
	v_and_b32_e32 v29, 0xffff0000, v67
	v_mul_f32_e32 v30, v23, v23
	v_mul_f32_e32 v31, v25, v25
	v_mul_f32_e32 v32, v27, v27
	v_mul_f32_e32 v33, v29, v29
	v_fmac_f32_e32 v30, v22, v22
	v_fmac_f32_e32 v31, v24, v24
	v_fmac_f32_e32 v32, v26, v26
	v_fmac_f32_e32 v33, v28, v28
	v_add_f32_e32 v126, v30, v31
	v_add_f32_e32 v126, v32, v126
	v_add_f32_e32 v126, v33, v126
	v_lshlrev_b32_e32 v22, 16, v68
	v_and_b32_e32 v23, 0xffff0000, v68
	v_lshlrev_b32_e32 v24, 16, v69
	v_and_b32_e32 v25, 0xffff0000, v69
	v_lshlrev_b32_e32 v26, 16, v70
	v_and_b32_e32 v27, 0xffff0000, v70
	v_lshlrev_b32_e32 v28, 16, v71
	v_and_b32_e32 v29, 0xffff0000, v71
	v_mul_f32_e32 v30, v23, v23
	v_mul_f32_e32 v31, v25, v25
	v_mul_f32_e32 v32, v27, v27
	v_mul_f32_e32 v33, v29, v29
	v_fmac_f32_e32 v30, v22, v22
	v_fmac_f32_e32 v31, v24, v24
	v_fmac_f32_e32 v32, v26, v26
	v_fmac_f32_e32 v33, v28, v28
	v_add_f32_e32 v119, v30, v31
	v_add_f32_e32 v119, v32, v119
	v_add_f32_e32 v119, v33, v119
	v_lshlrev_b32_e32 v22, 16, v72
	v_and_b32_e32 v23, 0xffff0000, v72
	v_lshlrev_b32_e32 v24, 16, v73
	v_and_b32_e32 v25, 0xffff0000, v73
	v_lshlrev_b32_e32 v26, 16, v74
	v_and_b32_e32 v27, 0xffff0000, v74
	v_lshlrev_b32_e32 v28, 16, v75
	v_and_b32_e32 v29, 0xffff0000, v75
	v_mul_f32_e32 v30, v23, v23
	v_mul_f32_e32 v31, v25, v25
	v_mul_f32_e32 v32, v27, v27
	v_mul_f32_e32 v33, v29, v29
	v_fmac_f32_e32 v30, v22, v22
	v_fmac_f32_e32 v31, v24, v24
	v_fmac_f32_e32 v32, v26, v26
	v_fmac_f32_e32 v33, v28, v28
	v_add_f32_e32 v127, v30, v31
	v_add_f32_e32 v127, v32, v127
	v_add_f32_e32 v127, v33, v127
	v_lshlrev_b32_e32 v22, 16, v76
	v_and_b32_e32 v23, 0xffff0000, v76
	v_lshlrev_b32_e32 v24, 16, v77
	v_and_b32_e32 v25, 0xffff0000, v77
	v_lshlrev_b32_e32 v26, 16, v78
	v_and_b32_e32 v27, 0xffff0000, v78
	v_lshlrev_b32_e32 v28, 16, v79
	v_and_b32_e32 v29, 0xffff0000, v79
	v_mul_f32_e32 v30, v23, v23
	v_mul_f32_e32 v31, v25, v25
	v_mul_f32_e32 v32, v27, v27
	v_mul_f32_e32 v33, v29, v29
	v_fmac_f32_e32 v30, v22, v22
	v_fmac_f32_e32 v31, v24, v24
	v_fmac_f32_e32 v32, v26, v26
	v_fmac_f32_e32 v33, v28, v28
	v_add_f32_e32 v120, v30, v31
	v_add_f32_e32 v120, v32, v120
	v_add_f32_e32 v120, v33, v120
	v_lshlrev_b32_e32 v22, 16, v80
	v_and_b32_e32 v23, 0xffff0000, v80
	v_lshlrev_b32_e32 v24, 16, v81
	v_and_b32_e32 v25, 0xffff0000, v81
	v_lshlrev_b32_e32 v26, 16, v82
	v_and_b32_e32 v27, 0xffff0000, v82
	v_lshlrev_b32_e32 v28, 16, v83
	v_and_b32_e32 v29, 0xffff0000, v83
	v_mul_f32_e32 v30, v23, v23
	v_mul_f32_e32 v31, v25, v25
	v_mul_f32_e32 v32, v27, v27
	v_mul_f32_e32 v33, v29, v29
	v_fmac_f32_e32 v30, v22, v22
	v_fmac_f32_e32 v31, v24, v24
	v_fmac_f32_e32 v32, v26, v26
	v_fmac_f32_e32 v33, v28, v28
	v_add_f32_e32 v128, v30, v31
	v_add_f32_e32 v128, v32, v128
	v_add_f32_e32 v128, v33, v128
	v_lshlrev_b32_e32 v22, 16, v84
	v_and_b32_e32 v23, 0xffff0000, v84
	v_lshlrev_b32_e32 v24, 16, v85
	v_and_b32_e32 v25, 0xffff0000, v85
	v_lshlrev_b32_e32 v26, 16, v86
	v_and_b32_e32 v27, 0xffff0000, v86
	v_lshlrev_b32_e32 v28, 16, v87
	v_and_b32_e32 v29, 0xffff0000, v87
	v_mul_f32_e32 v30, v23, v23
	v_mul_f32_e32 v31, v25, v25
	v_mul_f32_e32 v32, v27, v27
	v_mul_f32_e32 v33, v29, v29
	v_fmac_f32_e32 v30, v22, v22
	v_fmac_f32_e32 v31, v24, v24
	v_fmac_f32_e32 v32, v26, v26
	v_fmac_f32_e32 v33, v28, v28
	v_add_f32_e32 v121, v30, v31
	v_add_f32_e32 v121, v32, v121
	v_add_f32_e32 v121, v33, v121
	v_lshlrev_b32_e32 v22, 16, v88
	v_and_b32_e32 v23, 0xffff0000, v88
	v_lshlrev_b32_e32 v24, 16, v89
	v_and_b32_e32 v25, 0xffff0000, v89
	v_lshlrev_b32_e32 v26, 16, v90
	v_and_b32_e32 v27, 0xffff0000, v90
	v_lshlrev_b32_e32 v28, 16, v91
	v_and_b32_e32 v29, 0xffff0000, v91
	v_mul_f32_e32 v30, v23, v23
	v_mul_f32_e32 v31, v25, v25
	v_mul_f32_e32 v32, v27, v27
	v_mul_f32_e32 v33, v29, v29
	v_fmac_f32_e32 v30, v22, v22
	v_fmac_f32_e32 v31, v24, v24
	v_fmac_f32_e32 v32, v26, v26
	v_fmac_f32_e32 v33, v28, v28
	v_add_f32_e32 v129, v30, v31
	v_add_f32_e32 v129, v32, v129
	v_add_f32_e32 v129, v33, v129
	v_lshlrev_b32_e32 v22, 16, v92
	v_and_b32_e32 v23, 0xffff0000, v92
	v_lshlrev_b32_e32 v24, 16, v93
	v_and_b32_e32 v25, 0xffff0000, v93
	v_lshlrev_b32_e32 v26, 16, v94
	v_and_b32_e32 v27, 0xffff0000, v94
	v_lshlrev_b32_e32 v28, 16, v95
	v_and_b32_e32 v29, 0xffff0000, v95
	v_mul_f32_e32 v30, v23, v23
	v_mul_f32_e32 v31, v25, v25
	v_mul_f32_e32 v32, v27, v27
	v_mul_f32_e32 v33, v29, v29
	v_fmac_f32_e32 v30, v22, v22
	v_fmac_f32_e32 v31, v24, v24
	v_fmac_f32_e32 v32, v26, v26
	v_fmac_f32_e32 v33, v28, v28
	v_add_f32_e32 v122, v30, v31
	v_add_f32_e32 v122, v32, v122
	v_add_f32_e32 v122, v33, v122
	v_lshlrev_b32_e32 v22, 16, v96
	v_and_b32_e32 v23, 0xffff0000, v96
	v_lshlrev_b32_e32 v24, 16, v97
	v_and_b32_e32 v25, 0xffff0000, v97
	v_lshlrev_b32_e32 v26, 16, v98
	v_and_b32_e32 v27, 0xffff0000, v98
	v_lshlrev_b32_e32 v28, 16, v99
	v_and_b32_e32 v29, 0xffff0000, v99
	v_mul_f32_e32 v30, v23, v23
	v_mul_f32_e32 v31, v25, v25
	v_mul_f32_e32 v32, v27, v27
	v_mul_f32_e32 v33, v29, v29
	v_fmac_f32_e32 v30, v22, v22
	v_fmac_f32_e32 v31, v24, v24
	v_fmac_f32_e32 v32, v26, v26
	v_fmac_f32_e32 v33, v28, v28
	v_add_f32_e32 v130, v30, v31
	v_add_f32_e32 v130, v32, v130
	v_add_f32_e32 v130, v33, v130
	v_lshlrev_b32_e32 v22, 16, v100
	v_and_b32_e32 v23, 0xffff0000, v100
	v_lshlrev_b32_e32 v24, 16, v101
	v_and_b32_e32 v25, 0xffff0000, v101
	v_lshlrev_b32_e32 v26, 16, v102
	v_and_b32_e32 v27, 0xffff0000, v102
	v_lshlrev_b32_e32 v28, 16, v103
	v_and_b32_e32 v29, 0xffff0000, v103
	v_mul_f32_e32 v30, v23, v23
	v_mul_f32_e32 v31, v25, v25
	v_mul_f32_e32 v32, v27, v27
	v_mul_f32_e32 v33, v29, v29
	v_fmac_f32_e32 v30, v22, v22
	v_fmac_f32_e32 v31, v24, v24
	v_fmac_f32_e32 v32, v26, v26
	v_fmac_f32_e32 v33, v28, v28
	v_add_f32_e32 v123, v30, v31
	v_add_f32_e32 v123, v32, v123
	v_add_f32_e32 v123, v33, v123
	v_lshlrev_b32_e32 v22, 16, v104
	v_and_b32_e32 v23, 0xffff0000, v104
	v_lshlrev_b32_e32 v24, 16, v105
	v_and_b32_e32 v25, 0xffff0000, v105
	v_lshlrev_b32_e32 v26, 16, v106
	v_and_b32_e32 v27, 0xffff0000, v106
	v_lshlrev_b32_e32 v28, 16, v107
	v_and_b32_e32 v29, 0xffff0000, v107
	v_mul_f32_e32 v30, v23, v23
	v_mul_f32_e32 v31, v25, v25
	v_mul_f32_e32 v32, v27, v27
	v_mul_f32_e32 v33, v29, v29
	v_fmac_f32_e32 v30, v22, v22
	v_fmac_f32_e32 v31, v24, v24
	v_fmac_f32_e32 v32, v26, v26
	v_fmac_f32_e32 v33, v28, v28
	v_add_f32_e32 v131, v30, v31
	v_add_f32_e32 v131, v32, v131
	v_add_f32_e32 v131, v33, v131
	v_add_f32_dpp v116, v116, v116 quad_perm:[1,0,3,2] row_mask:0xf bank_mask:0xf bound_ctrl:1
	v_add_f32_dpp v117, v117, v117 quad_perm:[1,0,3,2] row_mask:0xf bank_mask:0xf bound_ctrl:1
	v_add_f32_dpp v118, v118, v118 quad_perm:[1,0,3,2] row_mask:0xf bank_mask:0xf bound_ctrl:1
	v_add_f32_dpp v119, v119, v119 quad_perm:[1,0,3,2] row_mask:0xf bank_mask:0xf bound_ctrl:1
	v_add_f32_dpp v120, v120, v120 quad_perm:[1,0,3,2] row_mask:0xf bank_mask:0xf bound_ctrl:1
	v_add_f32_dpp v121, v121, v121 quad_perm:[1,0,3,2] row_mask:0xf bank_mask:0xf bound_ctrl:1
	v_add_f32_dpp v122, v122, v122 quad_perm:[1,0,3,2] row_mask:0xf bank_mask:0xf bound_ctrl:1
	v_add_f32_dpp v123, v123, v123 quad_perm:[1,0,3,2] row_mask:0xf bank_mask:0xf bound_ctrl:1
	v_add_f32_dpp v124, v124, v124 quad_perm:[1,0,3,2] row_mask:0xf bank_mask:0xf bound_ctrl:1
	v_add_f32_dpp v125, v125, v125 quad_perm:[1,0,3,2] row_mask:0xf bank_mask:0xf bound_ctrl:1
	v_add_f32_dpp v126, v126, v126 quad_perm:[1,0,3,2] row_mask:0xf bank_mask:0xf bound_ctrl:1
	v_add_f32_dpp v127, v127, v127 quad_perm:[1,0,3,2] row_mask:0xf bank_mask:0xf bound_ctrl:1
	v_add_f32_dpp v128, v128, v128 quad_perm:[1,0,3,2] row_mask:0xf bank_mask:0xf bound_ctrl:1
	v_add_f32_dpp v129, v129, v129 quad_perm:[1,0,3,2] row_mask:0xf bank_mask:0xf bound_ctrl:1
	v_add_f32_dpp v130, v130, v130 quad_perm:[1,0,3,2] row_mask:0xf bank_mask:0xf bound_ctrl:1
	v_add_f32_dpp v131, v131, v131 quad_perm:[1,0,3,2] row_mask:0xf bank_mask:0xf bound_ctrl:1
	v_add_f32_dpp v116, v116, v116 quad_perm:[2,3,0,1] row_mask:0xf bank_mask:0xf bound_ctrl:1
	v_add_f32_dpp v117, v117, v117 quad_perm:[2,3,0,1] row_mask:0xf bank_mask:0xf bound_ctrl:1
	v_add_f32_dpp v118, v118, v118 quad_perm:[2,3,0,1] row_mask:0xf bank_mask:0xf bound_ctrl:1
	v_add_f32_dpp v119, v119, v119 quad_perm:[2,3,0,1] row_mask:0xf bank_mask:0xf bound_ctrl:1
	v_add_f32_dpp v120, v120, v120 quad_perm:[2,3,0,1] row_mask:0xf bank_mask:0xf bound_ctrl:1
	v_add_f32_dpp v121, v121, v121 quad_perm:[2,3,0,1] row_mask:0xf bank_mask:0xf bound_ctrl:1
	v_add_f32_dpp v122, v122, v122 quad_perm:[2,3,0,1] row_mask:0xf bank_mask:0xf bound_ctrl:1
	v_add_f32_dpp v123, v123, v123 quad_perm:[2,3,0,1] row_mask:0xf bank_mask:0xf bound_ctrl:1
	v_add_f32_dpp v124, v124, v124 quad_perm:[2,3,0,1] row_mask:0xf bank_mask:0xf bound_ctrl:1
	v_add_f32_dpp v125, v125, v125 quad_perm:[2,3,0,1] row_mask:0xf bank_mask:0xf bound_ctrl:1
	v_add_f32_dpp v126, v126, v126 quad_perm:[2,3,0,1] row_mask:0xf bank_mask:0xf bound_ctrl:1
	v_add_f32_dpp v127, v127, v127 quad_perm:[2,3,0,1] row_mask:0xf bank_mask:0xf bound_ctrl:1
	v_add_f32_dpp v128, v128, v128 quad_perm:[2,3,0,1] row_mask:0xf bank_mask:0xf bound_ctrl:1
	v_add_f32_dpp v129, v129, v129 quad_perm:[2,3,0,1] row_mask:0xf bank_mask:0xf bound_ctrl:1
	v_add_f32_dpp v130, v130, v130 quad_perm:[2,3,0,1] row_mask:0xf bank_mask:0xf bound_ctrl:1
	v_add_f32_dpp v131, v131, v131 quad_perm:[2,3,0,1] row_mask:0xf bank_mask:0xf bound_ctrl:1
	ds_bpermute_b32 v132, v6, v116
	ds_bpermute_b32 v133, v6, v117
	ds_bpermute_b32 v134, v6, v118
	ds_bpermute_b32 v135, v6, v119
	ds_bpermute_b32 v136, v6, v120
	ds_bpermute_b32 v137, v6, v121
	ds_bpermute_b32 v138, v6, v122
	ds_bpermute_b32 v139, v6, v123
	s_waitcnt lgkmcnt(0)
	v_add_f32_e32 v116, v116, v132
	v_add_f32_e32 v117, v117, v133
	v_add_f32_e32 v118, v118, v134
	v_add_f32_e32 v119, v119, v135
	v_add_f32_e32 v120, v120, v136
	v_add_f32_e32 v121, v121, v137
	v_add_f32_e32 v122, v122, v138
	v_add_f32_e32 v123, v123, v139
	ds_bpermute_b32 v132, v6, v124
	ds_bpermute_b32 v133, v6, v125
	ds_bpermute_b32 v134, v6, v126
	ds_bpermute_b32 v135, v6, v127
	ds_bpermute_b32 v136, v6, v128
	ds_bpermute_b32 v137, v6, v129
	ds_bpermute_b32 v138, v6, v130
	ds_bpermute_b32 v139, v6, v131
	s_waitcnt lgkmcnt(0)
	v_add_f32_e32 v124, v124, v132
	v_add_f32_e32 v125, v125, v133
	v_add_f32_e32 v126, v126, v134
	v_add_f32_e32 v127, v127, v135
	v_add_f32_e32 v128, v128, v136
	v_add_f32_e32 v129, v129, v137
	v_add_f32_e32 v130, v130, v138
	v_add_f32_e32 v131, v131, v139
	v_fmamk_f32 v116, v116, 0x3c800000, v198
	v_fmamk_f32 v117, v117, 0x3c800000, v198
	v_fmamk_f32 v118, v118, 0x3c800000, v198
	v_fmamk_f32 v119, v119, 0x3c800000, v198
	v_fmamk_f32 v120, v120, 0x3c800000, v198
	v_fmamk_f32 v121, v121, 0x3c800000, v198
	v_fmamk_f32 v122, v122, 0x3c800000, v198
	v_fmamk_f32 v123, v123, 0x3c800000, v198
	v_fmamk_f32 v124, v124, 0x3c800000, v198
	v_fmamk_f32 v125, v125, 0x3c800000, v198
	v_fmamk_f32 v126, v126, 0x3c800000, v198
	v_fmamk_f32 v127, v127, 0x3c800000, v198
	v_fmamk_f32 v128, v128, 0x3c800000, v198
	v_fmamk_f32 v129, v129, 0x3c800000, v198
	v_fmamk_f32 v130, v130, 0x3c800000, v198
	v_fmamk_f32 v131, v131, 0x3c800000, v198
	v_rsq_f32_e32 v116, v116
	v_rsq_f32_e32 v117, v117
	v_rsq_f32_e32 v118, v118
	v_rsq_f32_e32 v119, v119
	v_rsq_f32_e32 v120, v120
	v_rsq_f32_e32 v121, v121
	v_rsq_f32_e32 v122, v122
	v_rsq_f32_e32 v123, v123
	v_rsq_f32_e32 v124, v124
	v_rsq_f32_e32 v125, v125
	v_rsq_f32_e32 v126, v126
	v_rsq_f32_e32 v127, v127
	v_rsq_f32_e32 v128, v128
	v_rsq_f32_e32 v129, v129
	v_rsq_f32_e32 v130, v130
	v_rsq_f32_e32 v131, v131
	v_mul_f32_e32 v116, 0x3e38aa3b, v116
	v_mul_f32_e32 v117, 0x3e38aa3b, v117
	v_mul_f32_e32 v118, 0x3e38aa3b, v118
	v_mul_f32_e32 v119, 0x3e38aa3b, v119
	v_mul_f32_e32 v120, 0x3e38aa3b, v120
	v_mul_f32_e32 v121, 0x3e38aa3b, v121
	v_mul_f32_e32 v122, 0x3e38aa3b, v122
	v_mul_f32_e32 v123, 0x3e38aa3b, v123
	v_lshlrev_b32_e32 v22, 16, v44
	v_and_b32_e32 v23, 0xffff0000, v44
	v_lshlrev_b32_e32 v24, 16, v45
	v_and_b32_e32 v25, 0xffff0000, v45
	v_lshlrev_b32_e32 v26, 16, v46
	v_and_b32_e32 v27, 0xffff0000, v46
	v_lshlrev_b32_e32 v28, 16, v47
	v_and_b32_e32 v29, 0xffff0000, v47
	v_mov_b32_e32 v38, v116
	v_pk_mul_f32 v[30:31], v[212:213], v[22:23]
	v_pk_mul_f32 v[32:33], v[214:215], v[24:25]
	v_pk_mul_f32 v[34:35], v[216:217], v[26:27]
	v_pk_mul_f32 v[36:37], v[218:219], v[28:29]
	v_pk_mul_f32 v[30:31], v[30:31], v[38:39] op_sel_hi:[1,0]
	v_pk_mul_f32 v[32:33], v[32:33], v[38:39] op_sel_hi:[1,0]
	v_pk_mul_f32 v[34:35], v[34:35], v[38:39] op_sel_hi:[1,0]
	v_pk_mul_f32 v[36:37], v[36:37], v[38:39] op_sel_hi:[1,0]
	v_cvt_pk_bf16_f32 v44, v30, v31
	v_cvt_pk_bf16_f32 v45, v32, v33
	v_cvt_pk_bf16_f32 v46, v34, v35
	v_cvt_pk_bf16_f32 v47, v36, v37
	global_store_dwordx4 v108, v[44:47], s[36:37] offset:2048
	v_lshlrev_b32_e32 v22, 16, v48
	v_and_b32_e32 v23, 0xffff0000, v48
	v_lshlrev_b32_e32 v24, 16, v49
	v_and_b32_e32 v25, 0xffff0000, v49
	v_lshlrev_b32_e32 v26, 16, v50
	v_and_b32_e32 v27, 0xffff0000, v50
	v_lshlrev_b32_e32 v28, 16, v51
	v_and_b32_e32 v29, 0xffff0000, v51
	v_mov_b32_e32 v38, v124
	v_pk_mul_f32 v[30:31], v[220:221], v[22:23]
	v_pk_mul_f32 v[32:33], v[222:223], v[24:25]
	v_pk_mul_f32 v[34:35], v[224:225], v[26:27]
	v_pk_mul_f32 v[36:37], v[226:227], v[28:29]
	v_pk_mul_f32 v[30:31], v[30:31], v[38:39] op_sel_hi:[1,0]
	v_pk_mul_f32 v[32:33], v[32:33], v[38:39] op_sel_hi:[1,0]
	v_pk_mul_f32 v[34:35], v[34:35], v[38:39] op_sel_hi:[1,0]
	v_pk_mul_f32 v[36:37], v[36:37], v[38:39] op_sel_hi:[1,0]
	v_cvt_pk_bf16_f32 v48, v30, v31
	v_cvt_pk_bf16_f32 v49, v32, v33
	v_cvt_pk_bf16_f32 v50, v34, v35
	v_cvt_pk_bf16_f32 v51, v36, v37
	global_store_dwordx4 v108, v[48:51], s[36:37] offset:2560
	v_lshlrev_b32_e32 v22, 16, v52
	v_and_b32_e32 v23, 0xffff0000, v52
	v_lshlrev_b32_e32 v24, 16, v53
	v_and_b32_e32 v25, 0xffff0000, v53
	v_lshlrev_b32_e32 v26, 16, v54
	v_and_b32_e32 v27, 0xffff0000, v54
	v_lshlrev_b32_e32 v28, 16, v55
	v_and_b32_e32 v29, 0xffff0000, v55
	v_mov_b32_e32 v38, v117
	v_pk_mul_f32 v[30:31], v[212:213], v[22:23]
	v_pk_mul_f32 v[32:33], v[214:215], v[24:25]
	v_pk_mul_f32 v[34:35], v[216:217], v[26:27]
	v_pk_mul_f32 v[36:37], v[218:219], v[28:29]
	v_pk_mul_f32 v[30:31], v[30:31], v[38:39] op_sel_hi:[1,0]
	v_pk_mul_f32 v[32:33], v[32:33], v[38:39] op_sel_hi:[1,0]
	v_pk_mul_f32 v[34:35], v[34:35], v[38:39] op_sel_hi:[1,0]
	v_pk_mul_f32 v[36:37], v[36:37], v[38:39] op_sel_hi:[1,0]
	v_cvt_pk_bf16_f32 v52, v30, v31
	v_cvt_pk_bf16_f32 v53, v32, v33
	v_cvt_pk_bf16_f32 v54, v34, v35
	v_cvt_pk_bf16_f32 v55, v36, v37
	global_store_dwordx4 v109, v[52:55], s[36:37] offset:2048
	v_lshlrev_b32_e32 v22, 16, v56
	v_and_b32_e32 v23, 0xffff0000, v56
	v_lshlrev_b32_e32 v24, 16, v57
	v_and_b32_e32 v25, 0xffff0000, v57
	v_lshlrev_b32_e32 v26, 16, v58
	v_and_b32_e32 v27, 0xffff0000, v58
	v_lshlrev_b32_e32 v28, 16, v59
	v_and_b32_e32 v29, 0xffff0000, v59
	v_mov_b32_e32 v38, v125
	v_pk_mul_f32 v[30:31], v[220:221], v[22:23]
	v_pk_mul_f32 v[32:33], v[222:223], v[24:25]
	v_pk_mul_f32 v[34:35], v[224:225], v[26:27]
	v_pk_mul_f32 v[36:37], v[226:227], v[28:29]
	v_pk_mul_f32 v[30:31], v[30:31], v[38:39] op_sel_hi:[1,0]
	v_pk_mul_f32 v[32:33], v[32:33], v[38:39] op_sel_hi:[1,0]
	v_pk_mul_f32 v[34:35], v[34:35], v[38:39] op_sel_hi:[1,0]
	v_pk_mul_f32 v[36:37], v[36:37], v[38:39] op_sel_hi:[1,0]
	v_cvt_pk_bf16_f32 v56, v30, v31
	v_cvt_pk_bf16_f32 v57, v32, v33
	v_cvt_pk_bf16_f32 v58, v34, v35
	v_cvt_pk_bf16_f32 v59, v36, v37
	global_store_dwordx4 v109, v[56:59], s[36:37] offset:2560
	v_lshlrev_b32_e32 v22, 16, v60
	v_and_b32_e32 v23, 0xffff0000, v60
	v_lshlrev_b32_e32 v24, 16, v61
	v_and_b32_e32 v25, 0xffff0000, v61
	v_lshlrev_b32_e32 v26, 16, v62
	v_and_b32_e32 v27, 0xffff0000, v62
	v_lshlrev_b32_e32 v28, 16, v63
	v_and_b32_e32 v29, 0xffff0000, v63
	v_mov_b32_e32 v38, v118
	v_pk_mul_f32 v[30:31], v[212:213], v[22:23]
	v_pk_mul_f32 v[32:33], v[214:215], v[24:25]
	v_pk_mul_f32 v[34:35], v[216:217], v[26:27]
	v_pk_mul_f32 v[36:37], v[218:219], v[28:29]
	v_pk_mul_f32 v[30:31], v[30:31], v[38:39] op_sel_hi:[1,0]
	v_pk_mul_f32 v[32:33], v[32:33], v[38:39] op_sel_hi:[1,0]
	v_pk_mul_f32 v[34:35], v[34:35], v[38:39] op_sel_hi:[1,0]
	v_pk_mul_f32 v[36:37], v[36:37], v[38:39] op_sel_hi:[1,0]
	v_cvt_pk_bf16_f32 v60, v30, v31
	v_cvt_pk_bf16_f32 v61, v32, v33
	v_cvt_pk_bf16_f32 v62, v34, v35
	v_cvt_pk_bf16_f32 v63, v36, v37
	global_store_dwordx4 v110, v[60:63], s[36:37] offset:2048
	v_lshlrev_b32_e32 v22, 16, v64
	v_and_b32_e32 v23, 0xffff0000, v64
	v_lshlrev_b32_e32 v24, 16, v65
	v_and_b32_e32 v25, 0xffff0000, v65
	v_lshlrev_b32_e32 v26, 16, v66
	v_and_b32_e32 v27, 0xffff0000, v66
	v_lshlrev_b32_e32 v28, 16, v67
	v_and_b32_e32 v29, 0xffff0000, v67
	v_mov_b32_e32 v38, v126
	v_pk_mul_f32 v[30:31], v[220:221], v[22:23]
	v_pk_mul_f32 v[32:33], v[222:223], v[24:25]
	v_pk_mul_f32 v[34:35], v[224:225], v[26:27]
	v_pk_mul_f32 v[36:37], v[226:227], v[28:29]
	v_pk_mul_f32 v[30:31], v[30:31], v[38:39] op_sel_hi:[1,0]
	v_pk_mul_f32 v[32:33], v[32:33], v[38:39] op_sel_hi:[1,0]
	v_pk_mul_f32 v[34:35], v[34:35], v[38:39] op_sel_hi:[1,0]
	v_pk_mul_f32 v[36:37], v[36:37], v[38:39] op_sel_hi:[1,0]
	v_cvt_pk_bf16_f32 v64, v30, v31
	v_cvt_pk_bf16_f32 v65, v32, v33
	v_cvt_pk_bf16_f32 v66, v34, v35
	v_cvt_pk_bf16_f32 v67, v36, v37
	global_store_dwordx4 v110, v[64:67], s[36:37] offset:2560
	v_lshlrev_b32_e32 v22, 16, v68
	v_and_b32_e32 v23, 0xffff0000, v68
	v_lshlrev_b32_e32 v24, 16, v69
	v_and_b32_e32 v25, 0xffff0000, v69
	v_lshlrev_b32_e32 v26, 16, v70
	v_and_b32_e32 v27, 0xffff0000, v70
	v_lshlrev_b32_e32 v28, 16, v71
	v_and_b32_e32 v29, 0xffff0000, v71
	v_mov_b32_e32 v38, v119
	v_pk_mul_f32 v[30:31], v[212:213], v[22:23]
	v_pk_mul_f32 v[32:33], v[214:215], v[24:25]
	v_pk_mul_f32 v[34:35], v[216:217], v[26:27]
	v_pk_mul_f32 v[36:37], v[218:219], v[28:29]
	v_pk_mul_f32 v[30:31], v[30:31], v[38:39] op_sel_hi:[1,0]
	v_pk_mul_f32 v[32:33], v[32:33], v[38:39] op_sel_hi:[1,0]
	v_pk_mul_f32 v[34:35], v[34:35], v[38:39] op_sel_hi:[1,0]
	v_pk_mul_f32 v[36:37], v[36:37], v[38:39] op_sel_hi:[1,0]
	v_cvt_pk_bf16_f32 v68, v30, v31
	v_cvt_pk_bf16_f32 v69, v32, v33
	v_cvt_pk_bf16_f32 v70, v34, v35
	v_cvt_pk_bf16_f32 v71, v36, v37
	global_store_dwordx4 v111, v[68:71], s[36:37] offset:2048
	v_lshlrev_b32_e32 v22, 16, v72
	v_and_b32_e32 v23, 0xffff0000, v72
	v_lshlrev_b32_e32 v24, 16, v73
	v_and_b32_e32 v25, 0xffff0000, v73
	v_lshlrev_b32_e32 v26, 16, v74
	v_and_b32_e32 v27, 0xffff0000, v74
	v_lshlrev_b32_e32 v28, 16, v75
	v_and_b32_e32 v29, 0xffff0000, v75
	v_mov_b32_e32 v38, v127
	v_pk_mul_f32 v[30:31], v[220:221], v[22:23]
	v_pk_mul_f32 v[32:33], v[222:223], v[24:25]
	v_pk_mul_f32 v[34:35], v[224:225], v[26:27]
	v_pk_mul_f32 v[36:37], v[226:227], v[28:29]
	v_pk_mul_f32 v[30:31], v[30:31], v[38:39] op_sel_hi:[1,0]
	v_pk_mul_f32 v[32:33], v[32:33], v[38:39] op_sel_hi:[1,0]
	v_pk_mul_f32 v[34:35], v[34:35], v[38:39] op_sel_hi:[1,0]
	v_pk_mul_f32 v[36:37], v[36:37], v[38:39] op_sel_hi:[1,0]
	v_cvt_pk_bf16_f32 v72, v30, v31
	v_cvt_pk_bf16_f32 v73, v32, v33
	v_cvt_pk_bf16_f32 v74, v34, v35
	v_cvt_pk_bf16_f32 v75, v36, v37
	global_store_dwordx4 v111, v[72:75], s[36:37] offset:2560
	v_lshlrev_b32_e32 v22, 16, v76
	v_and_b32_e32 v23, 0xffff0000, v76
	v_lshlrev_b32_e32 v24, 16, v77
	v_and_b32_e32 v25, 0xffff0000, v77
	v_lshlrev_b32_e32 v26, 16, v78
	v_and_b32_e32 v27, 0xffff0000, v78
	v_lshlrev_b32_e32 v28, 16, v79
	v_and_b32_e32 v29, 0xffff0000, v79
	v_mov_b32_e32 v38, v120
	v_pk_mul_f32 v[30:31], v[212:213], v[22:23]
	v_pk_mul_f32 v[32:33], v[214:215], v[24:25]
	v_pk_mul_f32 v[34:35], v[216:217], v[26:27]
	v_pk_mul_f32 v[36:37], v[218:219], v[28:29]
	v_pk_mul_f32 v[30:31], v[30:31], v[38:39] op_sel_hi:[1,0]
	v_pk_mul_f32 v[32:33], v[32:33], v[38:39] op_sel_hi:[1,0]
	v_pk_mul_f32 v[34:35], v[34:35], v[38:39] op_sel_hi:[1,0]
	v_pk_mul_f32 v[36:37], v[36:37], v[38:39] op_sel_hi:[1,0]
	v_cvt_pk_bf16_f32 v76, v30, v31
	v_cvt_pk_bf16_f32 v77, v32, v33
	v_cvt_pk_bf16_f32 v78, v34, v35
	v_cvt_pk_bf16_f32 v79, v36, v37
	global_store_dwordx4 v112, v[76:79], s[36:37] offset:2048
	v_lshlrev_b32_e32 v22, 16, v80
	v_and_b32_e32 v23, 0xffff0000, v80
	v_lshlrev_b32_e32 v24, 16, v81
	v_and_b32_e32 v25, 0xffff0000, v81
	v_lshlrev_b32_e32 v26, 16, v82
	v_and_b32_e32 v27, 0xffff0000, v82
	v_lshlrev_b32_e32 v28, 16, v83
	v_and_b32_e32 v29, 0xffff0000, v83
	v_mov_b32_e32 v38, v128
	v_pk_mul_f32 v[30:31], v[220:221], v[22:23]
	v_pk_mul_f32 v[32:33], v[222:223], v[24:25]
	v_pk_mul_f32 v[34:35], v[224:225], v[26:27]
	v_pk_mul_f32 v[36:37], v[226:227], v[28:29]
	v_pk_mul_f32 v[30:31], v[30:31], v[38:39] op_sel_hi:[1,0]
	v_pk_mul_f32 v[32:33], v[32:33], v[38:39] op_sel_hi:[1,0]
	v_pk_mul_f32 v[34:35], v[34:35], v[38:39] op_sel_hi:[1,0]
	v_pk_mul_f32 v[36:37], v[36:37], v[38:39] op_sel_hi:[1,0]
	v_cvt_pk_bf16_f32 v80, v30, v31
	v_cvt_pk_bf16_f32 v81, v32, v33
	v_cvt_pk_bf16_f32 v82, v34, v35
	v_cvt_pk_bf16_f32 v83, v36, v37
	global_store_dwordx4 v112, v[80:83], s[36:37] offset:2560
	v_lshlrev_b32_e32 v22, 16, v84
	v_and_b32_e32 v23, 0xffff0000, v84
	v_lshlrev_b32_e32 v24, 16, v85
	v_and_b32_e32 v25, 0xffff0000, v85
	v_lshlrev_b32_e32 v26, 16, v86
	v_and_b32_e32 v27, 0xffff0000, v86
	v_lshlrev_b32_e32 v28, 16, v87
	v_and_b32_e32 v29, 0xffff0000, v87
	v_mov_b32_e32 v38, v121
	v_pk_mul_f32 v[30:31], v[212:213], v[22:23]
	v_pk_mul_f32 v[32:33], v[214:215], v[24:25]
	v_pk_mul_f32 v[34:35], v[216:217], v[26:27]
	v_pk_mul_f32 v[36:37], v[218:219], v[28:29]
	v_pk_mul_f32 v[30:31], v[30:31], v[38:39] op_sel_hi:[1,0]
	v_pk_mul_f32 v[32:33], v[32:33], v[38:39] op_sel_hi:[1,0]
	v_pk_mul_f32 v[34:35], v[34:35], v[38:39] op_sel_hi:[1,0]
	v_pk_mul_f32 v[36:37], v[36:37], v[38:39] op_sel_hi:[1,0]
	v_cvt_pk_bf16_f32 v84, v30, v31
	v_cvt_pk_bf16_f32 v85, v32, v33
	v_cvt_pk_bf16_f32 v86, v34, v35
	v_cvt_pk_bf16_f32 v87, v36, v37
	global_store_dwordx4 v113, v[84:87], s[36:37] offset:2048
	v_lshlrev_b32_e32 v22, 16, v88
	v_and_b32_e32 v23, 0xffff0000, v88
	v_lshlrev_b32_e32 v24, 16, v89
	v_and_b32_e32 v25, 0xffff0000, v89
	v_lshlrev_b32_e32 v26, 16, v90
	v_and_b32_e32 v27, 0xffff0000, v90
	v_lshlrev_b32_e32 v28, 16, v91
	v_and_b32_e32 v29, 0xffff0000, v91
	v_mov_b32_e32 v38, v129
	v_pk_mul_f32 v[30:31], v[220:221], v[22:23]
	v_pk_mul_f32 v[32:33], v[222:223], v[24:25]
	v_pk_mul_f32 v[34:35], v[224:225], v[26:27]
	v_pk_mul_f32 v[36:37], v[226:227], v[28:29]
	v_pk_mul_f32 v[30:31], v[30:31], v[38:39] op_sel_hi:[1,0]
	v_pk_mul_f32 v[32:33], v[32:33], v[38:39] op_sel_hi:[1,0]
	v_pk_mul_f32 v[34:35], v[34:35], v[38:39] op_sel_hi:[1,0]
	v_pk_mul_f32 v[36:37], v[36:37], v[38:39] op_sel_hi:[1,0]
	v_cvt_pk_bf16_f32 v88, v30, v31
	v_cvt_pk_bf16_f32 v89, v32, v33
	v_cvt_pk_bf16_f32 v90, v34, v35
	v_cvt_pk_bf16_f32 v91, v36, v37
	global_store_dwordx4 v113, v[88:91], s[36:37] offset:2560
	v_lshlrev_b32_e32 v22, 16, v92
	v_and_b32_e32 v23, 0xffff0000, v92
	v_lshlrev_b32_e32 v24, 16, v93
	v_and_b32_e32 v25, 0xffff0000, v93
	v_lshlrev_b32_e32 v26, 16, v94
	v_and_b32_e32 v27, 0xffff0000, v94
	v_lshlrev_b32_e32 v28, 16, v95
	v_and_b32_e32 v29, 0xffff0000, v95
	v_mov_b32_e32 v38, v122
	v_pk_mul_f32 v[30:31], v[212:213], v[22:23]
	v_pk_mul_f32 v[32:33], v[214:215], v[24:25]
	v_pk_mul_f32 v[34:35], v[216:217], v[26:27]
	v_pk_mul_f32 v[36:37], v[218:219], v[28:29]
	v_pk_mul_f32 v[30:31], v[30:31], v[38:39] op_sel_hi:[1,0]
	v_pk_mul_f32 v[32:33], v[32:33], v[38:39] op_sel_hi:[1,0]
	v_pk_mul_f32 v[34:35], v[34:35], v[38:39] op_sel_hi:[1,0]
	v_pk_mul_f32 v[36:37], v[36:37], v[38:39] op_sel_hi:[1,0]
	v_cvt_pk_bf16_f32 v92, v30, v31
	v_cvt_pk_bf16_f32 v93, v32, v33
	v_cvt_pk_bf16_f32 v94, v34, v35
	v_cvt_pk_bf16_f32 v95, v36, v37
	global_store_dwordx4 v114, v[92:95], s[36:37] offset:2048
	v_lshlrev_b32_e32 v22, 16, v96
	v_and_b32_e32 v23, 0xffff0000, v96
	v_lshlrev_b32_e32 v24, 16, v97
	v_and_b32_e32 v25, 0xffff0000, v97
	v_lshlrev_b32_e32 v26, 16, v98
	v_and_b32_e32 v27, 0xffff0000, v98
	v_lshlrev_b32_e32 v28, 16, v99
	v_and_b32_e32 v29, 0xffff0000, v99
	v_mov_b32_e32 v38, v130
	v_pk_mul_f32 v[30:31], v[220:221], v[22:23]
	v_pk_mul_f32 v[32:33], v[222:223], v[24:25]
	v_pk_mul_f32 v[34:35], v[224:225], v[26:27]
	v_pk_mul_f32 v[36:37], v[226:227], v[28:29]
	v_pk_mul_f32 v[30:31], v[30:31], v[38:39] op_sel_hi:[1,0]
	v_pk_mul_f32 v[32:33], v[32:33], v[38:39] op_sel_hi:[1,0]
	v_pk_mul_f32 v[34:35], v[34:35], v[38:39] op_sel_hi:[1,0]
	v_pk_mul_f32 v[36:37], v[36:37], v[38:39] op_sel_hi:[1,0]
	v_cvt_pk_bf16_f32 v96, v30, v31
	v_cvt_pk_bf16_f32 v97, v32, v33
	v_cvt_pk_bf16_f32 v98, v34, v35
	v_cvt_pk_bf16_f32 v99, v36, v37
	global_store_dwordx4 v114, v[96:99], s[36:37] offset:2560
	v_lshlrev_b32_e32 v22, 16, v100
	v_and_b32_e32 v23, 0xffff0000, v100
	v_lshlrev_b32_e32 v24, 16, v101
	v_and_b32_e32 v25, 0xffff0000, v101
	v_lshlrev_b32_e32 v26, 16, v102
	v_and_b32_e32 v27, 0xffff0000, v102
	v_lshlrev_b32_e32 v28, 16, v103
	v_and_b32_e32 v29, 0xffff0000, v103
	v_mov_b32_e32 v38, v123
	v_pk_mul_f32 v[30:31], v[212:213], v[22:23]
	v_pk_mul_f32 v[32:33], v[214:215], v[24:25]
	v_pk_mul_f32 v[34:35], v[216:217], v[26:27]
	v_pk_mul_f32 v[36:37], v[218:219], v[28:29]
	v_pk_mul_f32 v[30:31], v[30:31], v[38:39] op_sel_hi:[1,0]
	v_pk_mul_f32 v[32:33], v[32:33], v[38:39] op_sel_hi:[1,0]
	v_pk_mul_f32 v[34:35], v[34:35], v[38:39] op_sel_hi:[1,0]
	v_pk_mul_f32 v[36:37], v[36:37], v[38:39] op_sel_hi:[1,0]
	v_cvt_pk_bf16_f32 v100, v30, v31
	v_cvt_pk_bf16_f32 v101, v32, v33
	v_cvt_pk_bf16_f32 v102, v34, v35
	v_cvt_pk_bf16_f32 v103, v36, v37
	global_store_dwordx4 v115, v[100:103], s[36:37] offset:2048
	v_lshlrev_b32_e32 v22, 16, v104
	v_and_b32_e32 v23, 0xffff0000, v104
	v_lshlrev_b32_e32 v24, 16, v105
	v_and_b32_e32 v25, 0xffff0000, v105
	v_lshlrev_b32_e32 v26, 16, v106
	v_and_b32_e32 v27, 0xffff0000, v106
	v_lshlrev_b32_e32 v28, 16, v107
	v_and_b32_e32 v29, 0xffff0000, v107
	v_mov_b32_e32 v38, v131
	v_pk_mul_f32 v[30:31], v[220:221], v[22:23]
	v_pk_mul_f32 v[32:33], v[222:223], v[24:25]
	v_pk_mul_f32 v[34:35], v[224:225], v[26:27]
	v_pk_mul_f32 v[36:37], v[226:227], v[28:29]
	v_pk_mul_f32 v[30:31], v[30:31], v[38:39] op_sel_hi:[1,0]
	v_pk_mul_f32 v[32:33], v[32:33], v[38:39] op_sel_hi:[1,0]
	v_pk_mul_f32 v[34:35], v[34:35], v[38:39] op_sel_hi:[1,0]
	v_pk_mul_f32 v[36:37], v[36:37], v[38:39] op_sel_hi:[1,0]
	v_cvt_pk_bf16_f32 v104, v30, v31
	v_cvt_pk_bf16_f32 v105, v32, v33
	v_cvt_pk_bf16_f32 v106, v34, v35
	v_cvt_pk_bf16_f32 v107, v36, v37
	global_store_dwordx4 v115, v[104:107], s[36:37] offset:2560
	s_mov_b64 s[2:3], exec
